# MLA: second half of softmax1 moved behind the barrier under PV1 MFMAs; HGRN: next-stage loads stay in flight across the chunk loop, OUT rows via ds_write
# speedup vs baseline: 1.0366x; 1.0276x over previous
; DEV float bf2f(bf16_t b) { return __uint_as_float((unsigned)b << 16); }
; DEV unsigned pk2(float lo, float hi) { return pg8::cvt_pk_bf16(lo, hi); }
; DEV unsigned pk2b(float lo, float hi) { const f32x2 v = {lo, hi}; const bf16x2_t b = __builtin_convertvector(v, bf16x2_t); return __builtin_bit_cast(unsigned, b); }
; template <int PASS>
; DEV void hgrn_task(unsigned char* lds, int task, int l, const bf16_t* BZ, float* E, float* Dd, float* OF, bf16_t* YB, const float* b_lb, const float* gout) {
;     ...
;         for (int stg = 0; stg < 16; ++stg) {
;             const int g0 = stg * 64;
;             {
;                 float P = 1.f; float ki[16], pv[16];
; #pragma unroll
;                 for (int tp = 0; tp < 16; ++tp) { const float z = bf2f(zr[tp]);
;                     const float sp = __builtin_amdgcn_rcpf(1.f + __expf(-z)), sn = __builtin_amdgcn_rcpf(1.f + __expf(z)); const float f = lb + (1.f - lb) * sp, key = (1.f - lb) * sn;
;                     P *= f; const float kiv = key * __builtin_amdgcn_rcpf(fmaxf(P, 1e-36f)); ki[tp] = kiv;
;                     pv[tp] = P; }
;                 if (PASS == 3) {
; #pragma unroll
;                     for (int tp = 0; tp < 16; ++tp) { const float qd_ = bf2f(qr[tp]) * pv[tp]; QD[(pj * 16 + tp) * QP + pc] = (bf16_t)(pk2b(qd_, 0.f) & 0xffffu); KI[(pj * 16 + tp) * QP + pc] = (bf16_t)(pk2b(ki[tp], 0.f) & 0xffffu); } }
;                 u32x4 w0, w1;
;                 w0.x = pk2(ki[0] * P, ki[1] * P); w0.y = pk2(ki[2] * P, ki[3] * P); w0.z = pk2(ki[4] * P, ki[5] * P); w0.w = pk2(ki[6] * P, ki[7] * P);
;                 w1.x = pk2(ki[8] * P, ki[9] * P); w1.y = pk2(ki[10] * P, ki[11] * P); w1.z = pk2(ki[12] * P, ki[13] * P); w1.w = pk2(ki[14] * P, ki[15] * P);
;                 *(u32x4*)(KET + (pj * 128 + pc) * 16) = w0; *(u32x4*)(KET + (pj * 128 + pc) * 16 + 8) = w1;
;                 DEC[pj * 128 + pc] = P; if (PASS == 1) dprod *= P;
;                 u32x4 vw; vw.x = vv[0] | ((unsigned)vv[1] << 16); vw.y = vv[2] | ((unsigned)vv[3] << 16); vw.z = vv[4] | ((unsigned)vv[5] << 16); vw.w = vv[6] | ((unsigned)vv[7] << 16);
.LBB0_497:
	s_waitcnt vmcnt(0)
	v_perm_b32 v32, v244, v243, s63
	v_perm_b32 v33, v246, v245, s63
	v_perm_b32 v34, v248, v247, s63
	v_perm_b32 v35, v35, v250, s63
	s_add_i32 s19, s19, 1
	v_mul_f32_e32 v117, v117, v50
	s_cmp_eq_u32 s19, 16
	s_barrier
	s_cbranch_scc1 .LBB0_503
.LBB0_498:
	v_lshlrev_b32_e32 v45, 16, v113
	v_mul_f32_e32 v49, 0xbfb8aa3b, v45
	v_exp_f32_e32 v49, v49
	v_mul_f32_e32 v45, 0x3fb8aa3b, v45
	v_exp_f32_e32 v45, v45
	v_lshlrev_b32_e32 v134, 16, v116
	v_add_f32_e32 v49, 1.0, v49
	v_rcp_f32_e32 v49, v49
	v_add_f32_e32 v45, 1.0, v45
	v_rcp_f32_e32 v45, v45
	s_cmp_eq_u32 s19, 15
	v_fma_f32 v51, v48, v49, v44
	v_max_f32_e32 v49, 0x3aa2425, v51
	v_rcp_f32_e32 v49, v49
	v_mul_f32_e32 v45, v48, v45
	v_mul_f32_e32 v126, v45, v49
	v_lshlrev_b32_e32 v45, 16, v114
	v_mul_f32_e32 v49, 0xbfb8aa3b, v45
	v_mul_f32_e32 v45, 0x3fb8aa3b, v45
	v_exp_f32_e32 v45, v45
	v_exp_f32_e32 v49, v49
	v_add_f32_e32 v45, 1.0, v45
	v_rcp_f32_e32 v45, v45
	v_add_f32_e32 v49, 1.0, v49
	v_rcp_f32_e32 v49, v49
	v_mul_f32_e32 v127, v48, v45
	v_lshlrev_b32_e32 v45, 16, v115
	v_mul_f32_e32 v50, 0xbfb8aa3b, v45
	v_exp_f32_e32 v50, v50
	v_mul_f32_e32 v45, 0x3fb8aa3b, v45
	v_exp_f32_e32 v45, v45
	v_fma_f32 v49, v48, v49, v44
	v_add_f32_e32 v50, 1.0, v50
	v_rcp_f32_e32 v50, v50
	v_add_f32_e32 v45, 1.0, v45
	v_rcp_f32_e32 v129, v45
	v_fma_f32 v45, v48, v50, v44
	v_mul_f32_e32 v50, 0xbfb8aa3b, v134
	v_exp_f32_e32 v50, v50
	v_mul_f32_e32 v134, 0x3fb8aa3b, v134
	v_exp_f32_e32 v134, v134
	v_mul_f32_e32 v129, v48, v129
	v_add_f32_e32 v50, 1.0, v50
	v_rcp_f32_e32 v50, v50
	v_add_f32_e32 v134, 1.0, v134
	v_rcp_f32_e32 v136, v134
	v_pk_mul_f32 v[134:135], v[48:49], v[50:51]
	s_nop 0
	v_max_f32_e32 v137, 0x3aa2425, v135
	v_pk_fma_f32 v[50:51], v[48:49], v[50:51], v[44:45]
	v_pk_mul_f32 v[134:135], v[44:45], v[134:135]
	v_rcp_f32_e32 v137, v137
	v_max_f32_e32 v45, 0x3aa2425, v135
	v_pk_mul_f32 v[50:51], v[50:51], v[134:135] op_sel:[0,1] op_sel_hi:[1,0]
	v_rcp_f32_e32 v45, v45
	v_max_f32_e32 v49, 0x3aa2425, v50
	v_rcp_f32_e32 v49, v49
	v_mul_f32_e32 v127, v127, v137
	v_mul_f32_e32 v129, v129, v45
	v_mul_f32_e32 v45, v48, v136
	v_mul_f32_e32 v134, v45, v49
	v_lshlrev_b32_e32 v45, 16, v118
	v_mul_f32_e32 v49, 0xbfb8aa3b, v45
	v_mul_f32_e32 v45, 0x3fb8aa3b, v45
	v_exp_f32_e32 v45, v45
	v_exp_f32_e32 v49, v49
	v_mov_b32_e32 v137, v50
	v_add_f32_e32 v45, 1.0, v45
	v_rcp_f32_e32 v45, v45
	v_add_f32_e32 v49, 1.0, v49
	v_rcp_f32_e32 v49, v49
	v_mul_f32_e32 v135, v48, v45
	v_lshlrev_b32_e32 v45, 16, v119
	v_mul_f32_e32 v51, 0xbfb8aa3b, v45
	v_exp_f32_e32 v51, v51
	v_mul_f32_e32 v45, 0x3fb8aa3b, v45
	v_exp_f32_e32 v45, v45
	v_fma_f32 v49, v48, v49, v44
	v_add_f32_e32 v51, 1.0, v51
	v_rcp_f32_e32 v51, v51
	v_add_f32_e32 v45, 1.0, v45
	v_rcp_f32_e32 v136, v45
	v_fma_f32 v45, v48, v51, v44
	v_lshlrev_b32_e32 v51, 16, v120
	v_mul_f32_e32 v140, v48, v136
	v_mul_f32_e32 v136, 0xbfb8aa3b, v51
	v_exp_f32_e32 v136, v136
	v_mul_f32_e32 v51, 0x3fb8aa3b, v51
	v_exp_f32_e32 v51, v51
	v_add_f32_e32 v136, 1.0, v136
	v_rcp_f32_e32 v136, v136
	v_add_f32_e32 v51, 1.0, v51
	v_rcp_f32_e32 v141, v51
	v_pk_mul_f32 v[50:51], v[48:49], v[136:137]
	s_nop 0
	v_max_f32_e32 v138, 0x3aa2425, v51
	v_rcp_f32_e32 v138, v138
	v_pk_mul_f32 v[50:51], v[44:45], v[50:51]
	v_mul_f32_e32 v135, v135, v138
	v_pk_fma_f32 v[138:139], v[48:49], v[136:137], v[44:45]
	v_max_f32_e32 v45, 0x3aa2425, v51
	v_pk_mul_f32 v[50:51], v[138:139], v[50:51] op_sel:[0,1] op_sel_hi:[1,0]
	v_rcp_f32_e32 v45, v45
	v_max_f32_e32 v49, 0x3aa2425, v50
	v_rcp_f32_e32 v49, v49
	v_mov_b32_e32 v139, v50
	v_mul_f32_e32 v136, v140, v45
	v_mul_f32_e32 v45, v48, v141
	v_mul_f32_e32 v137, v45, v49
	v_lshlrev_b32_e32 v45, 16, v121
	v_mul_f32_e32 v49, 0xbfb8aa3b, v45
	v_mul_f32_e32 v45, 0x3fb8aa3b, v45
	v_exp_f32_e32 v45, v45
	v_exp_f32_e32 v49, v49
	v_add_f32_e32 v45, 1.0, v45
	v_rcp_f32_e32 v45, v45
	v_add_f32_e32 v49, 1.0, v49
	v_rcp_f32_e32 v49, v49
	v_mul_f32_e32 v140, v48, v45
	v_lshlrev_b32_e32 v45, 16, v122
	v_mul_f32_e32 v51, 0xbfb8aa3b, v45
	v_exp_f32_e32 v51, v51
	v_mul_f32_e32 v45, 0x3fb8aa3b, v45
	v_exp_f32_e32 v45, v45
	v_fma_f32 v49, v48, v49, v44
	v_add_f32_e32 v51, 1.0, v51
	v_rcp_f32_e32 v51, v51
	v_add_f32_e32 v45, 1.0, v45
	v_rcp_f32_e32 v138, v45
	v_fma_f32 v45, v48, v51, v44
	v_lshlrev_b32_e32 v51, 16, v123
	v_mul_f32_e32 v141, v48, v138
	v_mul_f32_e32 v138, 0xbfb8aa3b, v51
	v_exp_f32_e32 v138, v138
	v_mul_f32_e32 v51, 0x3fb8aa3b, v51
	v_exp_f32_e32 v51, v51
	v_add_f32_e32 v138, 1.0, v138
	v_rcp_f32_e32 v138, v138
	v_add_f32_e32 v51, 1.0, v51
	v_rcp_f32_e32 v142, v51
	v_pk_mul_f32 v[50:51], v[48:49], v[138:139]
	s_nop 0
	v_max_f32_e32 v143, 0x3aa2425, v51
	v_pk_fma_f32 v[138:139], v[48:49], v[138:139], v[44:45]
	v_pk_mul_f32 v[50:51], v[44:45], v[50:51]
	v_rcp_f32_e32 v143, v143
	v_max_f32_e32 v45, 0x3aa2425, v51
	v_pk_mul_f32 v[50:51], v[138:139], v[50:51] op_sel:[0,1] op_sel_hi:[1,0]
	v_rcp_f32_e32 v45, v45
	v_max_f32_e32 v49, 0x3aa2425, v50
	v_rcp_f32_e32 v49, v49
	v_mul_f32_e32 v143, v140, v143
	v_mul_f32_e32 v144, v141, v45
	v_mul_f32_e32 v45, v48, v142
	v_mul_f32_e32 v142, v45, v49
	v_lshlrev_b32_e32 v45, 16, v124
	v_mul_f32_e32 v49, 0xbfb8aa3b, v45
	v_mul_f32_e32 v45, 0x3fb8aa3b, v45
	v_exp_f32_e32 v45, v45
	v_exp_f32_e32 v49, v49
	v_mov_b32_e32 v139, v50
	v_add_f32_e32 v45, 1.0, v45
	v_rcp_f32_e32 v45, v45
	v_add_f32_e32 v49, 1.0, v49
	v_rcp_f32_e32 v49, v49
	v_mul_f32_e32 v140, v48, v45
	v_lshlrev_b32_e32 v45, 16, v125
	v_mul_f32_e32 v51, 0xbfb8aa3b, v45
	v_exp_f32_e32 v51, v51
	v_mul_f32_e32 v45, 0x3fb8aa3b, v45
	v_exp_f32_e32 v45, v45
	v_fma_f32 v49, v48, v49, v44
	v_add_f32_e32 v51, 1.0, v51
	v_rcp_f32_e32 v51, v51
; DEV float bf2f(bf16_t b) { return __uint_as_float((unsigned)b << 16); }
; DEV unsigned pk2(float lo, float hi) { return pg8::cvt_pk_bf16(lo, hi); }
; DEV unsigned pk2b(float lo, float hi) { const f32x2 v = {lo, hi}; const bf16x2_t b = __builtin_convertvector(v, bf16x2_t); return __builtin_bit_cast(unsigned, b); }
; template <int PASS>
; DEV void hgrn_task(unsigned char* lds, int task, int l, const bf16_t* BZ, float* E, float* Dd, float* OF, bf16_t* YB, const float* b_lb, const float* gout) {
;     ...
;                 for (int tp = 0; tp < 16; ++tp) { const float z = bf2f(zr[tp]);
;                     const float sp = __builtin_amdgcn_rcpf(1.f + __expf(-z)), sn = __builtin_amdgcn_rcpf(1.f + __expf(z)); const float f = lb + (1.f - lb) * sp, key = (1.f - lb) * sn;
;                     P *= f; const float kiv = key * __builtin_amdgcn_rcpf(fmaxf(P, 1e-36f)); ki[tp] = kiv;
;                     pv[tp] = P; }
;                 if (PASS == 3) {
; #pragma unroll
;                     for (int tp = 0; tp < 16; ++tp) { const float qd_ = bf2f(qr[tp]) * pv[tp]; QD[(pj * 16 + tp) * QP + pc] = (bf16_t)(pk2b(qd_, 0.f) & 0xffffu); KI[(pj * 16 + tp) * QP + pc] = (bf16_t)(pk2b(ki[tp], 0.f) & 0xffffu); } }
;                 u32x4 w0, w1;
;                 w0.x = pk2(ki[0] * P, ki[1] * P); w0.y = pk2(ki[2] * P, ki[3] * P); w0.z = pk2(ki[4] * P, ki[5] * P); w0.w = pk2(ki[6] * P, ki[7] * P);
;                 w1.x = pk2(ki[8] * P, ki[9] * P); w1.y = pk2(ki[10] * P, ki[11] * P); w1.z = pk2(ki[12] * P, ki[13] * P); w1.w = pk2(ki[14] * P, ki[15] * P);
;                 *(u32x4*)(KET + (pj * 128 + pc) * 16) = w0; *(u32x4*)(KET + (pj * 128 + pc) * 16 + 8) = w1;
;                 DEC[pj * 128 + pc] = P; if (PASS == 1) dprod *= P;
;                 u32x4 vw; vw.x = vv[0] | ((unsigned)vv[1] << 16); vw.y = vv[2] | ((unsigned)vv[3] << 16); vw.z = vv[4] | ((unsigned)vv[5] << 16); vw.w = vv[6] | ((unsigned)vv[7] << 16);
;                 *(u32x4*)(VT + (pj * 64 + vn) * 16 + vsh * 8) = vw;
;             }
;             __syncthreads();
	v_add_f32_e32 v45, 1.0, v45
	v_rcp_f32_e32 v138, v45
	v_fma_f32 v45, v48, v51, v44
	v_lshlrev_b32_e32 v51, 16, v130
	v_mul_f32_e32 v141, v48, v138
	v_mul_f32_e32 v138, 0xbfb8aa3b, v51
	v_exp_f32_e32 v138, v138
	v_mul_f32_e32 v51, 0x3fb8aa3b, v51
	v_exp_f32_e32 v51, v51
	v_add_f32_e32 v138, 1.0, v138
	v_rcp_f32_e32 v138, v138
	v_add_f32_e32 v51, 1.0, v51
	v_rcp_f32_e32 v145, v51
	v_pk_mul_f32 v[50:51], v[48:49], v[138:139]
	s_nop 0
	v_max_f32_e32 v146, 0x3aa2425, v51
	v_pk_fma_f32 v[138:139], v[48:49], v[138:139], v[44:45]
	v_pk_mul_f32 v[50:51], v[44:45], v[50:51]
	v_rcp_f32_e32 v146, v146
	v_max_f32_e32 v45, 0x3aa2425, v51
	v_pk_mul_f32 v[50:51], v[138:139], v[50:51] op_sel:[0,1] op_sel_hi:[1,0]
	v_rcp_f32_e32 v45, v45
	v_max_f32_e32 v49, 0x3aa2425, v50
	v_rcp_f32_e32 v49, v49
	v_mul_f32_e32 v146, v140, v146
	v_mul_f32_e32 v147, v141, v45
	v_mul_f32_e32 v45, v48, v145
	v_mul_f32_e32 v145, v45, v49
	v_lshlrev_b32_e32 v45, 16, v131
	v_mul_f32_e32 v49, 0xbfb8aa3b, v45
	v_mul_f32_e32 v45, 0x3fb8aa3b, v45
	v_exp_f32_e32 v45, v45
	v_exp_f32_e32 v49, v49
	v_mov_b32_e32 v139, v50
	v_add_f32_e32 v45, 1.0, v45
	v_rcp_f32_e32 v45, v45
	v_add_f32_e32 v49, 1.0, v49
	v_rcp_f32_e32 v49, v49
	v_mul_f32_e32 v140, v48, v45
	v_lshlrev_b32_e32 v45, 16, v132
	v_mul_f32_e32 v51, 0xbfb8aa3b, v45
	v_exp_f32_e32 v51, v51
	v_mul_f32_e32 v45, 0x3fb8aa3b, v45
	v_exp_f32_e32 v45, v45
	v_fma_f32 v49, v48, v49, v44
	v_add_f32_e32 v51, 1.0, v51
	v_rcp_f32_e32 v51, v51
	v_add_f32_e32 v45, 1.0, v45
	v_rcp_f32_e32 v138, v45
	v_fma_f32 v45, v48, v51, v44
	v_lshlrev_b32_e32 v51, 16, v133
	v_mul_f32_e32 v148, v48, v138
	v_mul_f32_e32 v138, 0xbfb8aa3b, v51
	v_exp_f32_e32 v138, v138
	v_mul_f32_e32 v51, 0x3fb8aa3b, v51
	v_exp_f32_e32 v51, v51
	v_add_f32_e32 v138, 1.0, v138
	v_rcp_f32_e32 v138, v138
	v_add_f32_e32 v51, 1.0, v51
	v_rcp_f32_e32 v149, v51
	v_pk_mul_f32 v[50:51], v[48:49], v[138:139]
	s_nop 0
	v_max_f32_e32 v141, 0x3aa2425, v51
	v_rcp_f32_e32 v141, v141
	v_pk_mul_f32 v[50:51], v[44:45], v[50:51]
	v_pk_fma_f32 v[138:139], v[48:49], v[138:139], v[44:45]
	v_max_f32_e32 v45, 0x3aa2425, v51
	v_mul_f32_e32 v150, v140, v141
	v_rcp_f32_e32 v141, v45
	v_mov_b32_e32 v139, v148
	v_mov_b32_e32 v140, v51
	v_mul_f32_e32 v45, v48, v149
	v_pk_mul_f32 v[50:51], v[138:139], v[140:141]
	s_nop 0
	v_max_f32_e32 v49, 0x3aa2425, v50
	v_rcp_f32_e32 v49, v49
	s_nop 0
	v_mul_f32_e32 v45, v45, v49
	v_mul_f32_e32 v49, v126, v50
	v_mul_f32_e32 v126, v127, v50
	v_cvt_pk_bf16_f32 v138, v49, v126
	v_mul_f32_e32 v49, v129, v50
	v_mul_f32_e32 v126, v134, v50
	v_cvt_pk_bf16_f32 v139, v49, v126
	v_mul_f32_e32 v49, v135, v50
	v_mul_f32_e32 v126, v136, v50
	v_cvt_pk_bf16_f32 v140, v49, v126
	v_mul_f32_e32 v49, v137, v50
	v_mul_f32_e32 v126, v143, v50
	v_cvt_pk_bf16_f32 v141, v49, v126
	v_mul_f32_e32 v49, v144, v50
	v_mul_f32_e32 v126, v142, v50
	v_cvt_pk_bf16_f32 v134, v49, v126
	v_mul_f32_e32 v49, v146, v50
	v_mul_f32_e32 v126, v147, v50
	v_cvt_pk_bf16_f32 v135, v49, v126
	v_mul_f32_e32 v49, v145, v50
	v_mul_f32_e32 v126, v50, v150
	v_cvt_pk_bf16_f32 v136, v49, v126
	v_mul_f32_e32 v49, v50, v51
	v_mul_f32_e32 v45, v50, v45
	v_cvt_pk_bf16_f32 v137, v49, v45
	ds_write_b128 v57, v[138:141] offset:34816
	ds_write_b128 v57, v[134:137] offset:34832
	ds_write_b32 v112, v50 offset:59392
	ds_write_b128 v58, v[32:35] offset:51200
	s_waitcnt lgkmcnt(0)
	s_barrier
	s_cbranch_scc1 .LBB0_500
; #define HLOADS(g0_) do { _Pragma("unroll") for (int tp = 0; tp < 16; ++tp) { const size_t rb = (size_t)HROW((g0_) + pj * 16 + tp) * 4096; zr[tp] = zb[rb]; if (PASS == 3) qr[tp] = qb[rb]; } \
;             _Pragma("unroll") for (int s8 = 0; s8 < 8; ++s8) vv[s8] = vb[(size_t)HROW((g0_) + pj * 16 + vsh * 8 + s8) * 4096]; } while (0)
; template <int PASS>
; DEV void hgrn_task(unsigned char* lds, int task, int l, const bf16_t* BZ, float* E, float* Dd, float* OF, bf16_t* YB, const float* b_lb, const float* gout) {
;     ...
;             if (stg + 1 < 16) HLOADS(g0 + 64);
	s_lshl_b32 s5, s19, 6
	v_add_u32_e32 v34, s5, v53
	v_add_u32_e32 v35, s5, v59
	v_sub_u32_e32 v32, s28, v34
	v_cndmask_b32_e64 v32, v32, v35, s[16:17]
	v_ashrrev_i32_e32 v33, 31, v32
	v_lshlrev_b64 v[32:33], 13, v[32:33]
	v_lshl_add_u64 v[32:33], v[46:47], 0, v[32:33]
	global_load_ushort v113, v[32:33], off
	v_xad_u32 v32, v34, -1, s28
	v_or_b32_e32 v33, 1, v35
	v_cndmask_b32_e64 v32, v32, v33, s[16:17]
	v_ashrrev_i32_e32 v33, 31, v32
	v_lshlrev_b64 v[32:33], 13, v[32:33]
	v_lshl_add_u64 v[32:33], v[46:47], 0, v[32:33]
	global_load_ushort v114, v[32:33], off
	v_sub_u32_e32 v32, s29, v34
	v_or_b32_e32 v33, 2, v35
	v_cndmask_b32_e64 v32, v32, v33, s[16:17]
	v_ashrrev_i32_e32 v33, 31, v32
	v_lshlrev_b64 v[32:33], 13, v[32:33]
	v_lshl_add_u64 v[32:33], v[46:47], 0, v[32:33]
	global_load_ushort v115, v[32:33], off
	v_sub_u32_e32 v32, s30, v34
	v_or_b32_e32 v33, 3, v35
	v_cndmask_b32_e64 v32, v32, v33, s[16:17]
	v_ashrrev_i32_e32 v33, 31, v32
	v_lshlrev_b64 v[32:33], 13, v[32:33]
	v_lshl_add_u64 v[32:33], v[46:47], 0, v[32:33]
	global_load_ushort v116, v[32:33], off
	v_sub_u32_e32 v32, s31, v34
	v_or_b32_e32 v33, 4, v35
	v_cndmask_b32_e64 v32, v32, v33, s[16:17]
	v_ashrrev_i32_e32 v33, 31, v32
	v_lshlrev_b64 v[32:33], 13, v[32:33]
	v_lshl_add_u64 v[32:33], v[46:47], 0, v[32:33]
	global_load_ushort v118, v[32:33], off
	v_sub_u32_e32 v32, s34, v34
	v_or_b32_e32 v33, 5, v35
	v_cndmask_b32_e64 v32, v32, v33, s[16:17]
	v_ashrrev_i32_e32 v33, 31, v32
	v_lshlrev_b64 v[32:33], 13, v[32:33]
	v_lshl_add_u64 v[32:33], v[46:47], 0, v[32:33]
	global_load_ushort v119, v[32:33], off
	v_sub_u32_e32 v32, s35, v34
	v_or_b32_e32 v33, 6, v35
	v_cndmask_b32_e64 v32, v32, v33, s[16:17]
	v_ashrrev_i32_e32 v33, 31, v32
	v_lshlrev_b64 v[32:33], 13, v[32:33]
	v_lshl_add_u64 v[32:33], v[46:47], 0, v[32:33]
	global_load_ushort v120, v[32:33], off
	v_sub_u32_e32 v32, s36, v34
	v_or_b32_e32 v33, 7, v35
	v_cndmask_b32_e64 v32, v32, v33, s[16:17]
	v_ashrrev_i32_e32 v33, 31, v32
	v_lshlrev_b64 v[32:33], 13, v[32:33]
	v_lshl_add_u64 v[32:33], v[46:47], 0, v[32:33]
	global_load_ushort v121, v[32:33], off
	v_sub_u32_e32 v32, s37, v34
	v_or_b32_e32 v33, 8, v35
	v_cndmask_b32_e64 v32, v32, v33, s[16:17]
	v_ashrrev_i32_e32 v33, 31, v32
	v_lshlrev_b64 v[32:33], 13, v[32:33]
	v_lshl_add_u64 v[32:33], v[46:47], 0, v[32:33]
	global_load_ushort v122, v[32:33], off
	v_sub_u32_e32 v32, s38, v34
	v_or_b32_e32 v33, 9, v35
	v_cndmask_b32_e64 v32, v32, v33, s[16:17]
	v_ashrrev_i32_e32 v33, 31, v32
	v_lshlrev_b64 v[32:33], 13, v[32:33]
	v_lshl_add_u64 v[32:33], v[46:47], 0, v[32:33]
	global_load_ushort v123, v[32:33], off
	v_sub_u32_e32 v32, s39, v34
	v_or_b32_e32 v33, 10, v35
	v_cndmask_b32_e64 v32, v32, v33, s[16:17]
	v_ashrrev_i32_e32 v33, 31, v32
	v_lshlrev_b64 v[32:33], 13, v[32:33]
	v_lshl_add_u64 v[32:33], v[46:47], 0, v[32:33]
	global_load_ushort v124, v[32:33], off
	v_sub_u32_e32 v32, s48, v34
	v_or_b32_e32 v33, 11, v35
	v_cndmask_b32_e64 v32, v32, v33, s[16:17]
	v_ashrrev_i32_e32 v33, 31, v32
	v_lshlrev_b64 v[32:33], 13, v[32:33]
	v_lshl_add_u64 v[32:33], v[46:47], 0, v[32:33]
	global_load_ushort v125, v[32:33], off
	v_sub_u32_e32 v32, s49, v34
	v_or_b32_e32 v33, 12, v35
	v_cndmask_b32_e64 v32, v32, v33, s[16:17]
	v_ashrrev_i32_e32 v33, 31, v32
	v_lshlrev_b64 v[32:33], 13, v[32:33]
	v_lshl_add_u64 v[32:33], v[46:47], 0, v[32:33]
	global_load_ushort v130, v[32:33], off
	v_sub_u32_e32 v32, s54, v34
	v_or_b32_e32 v33, 13, v35
	v_cndmask_b32_e64 v32, v32, v33, s[16:17]
	v_ashrrev_i32_e32 v33, 31, v32
	v_lshlrev_b64 v[32:33], 13, v[32:33]
	v_lshl_add_u64 v[32:33], v[46:47], 0, v[32:33]
	global_load_ushort v131, v[32:33], off
	v_sub_u32_e32 v32, s55, v34
	v_or_b32_e32 v33, 14, v35
	v_cndmask_b32_e64 v32, v32, v33, s[16:17]
	v_ashrrev_i32_e32 v33, 31, v32
	v_lshlrev_b64 v[32:33], 13, v[32:33]
	v_lshl_add_u64 v[32:33], v[46:47], 0, v[32:33]
	global_load_ushort v132, v[32:33], off
	v_sub_u32_e32 v32, s64, v34
	v_or_b32_e32 v33, 15, v35
	v_cndmask_b32_e64 v32, v32, v33, s[16:17]
	v_ashrrev_i32_e32 v33, 31, v32
	v_lshlrev_b64 v[32:33], 13, v[32:33]
	v_lshl_add_u64 v[32:33], v[46:47], 0, v[32:33]
	global_load_ushort v133, v[32:33], off
	v_or_b32_e32 v32, s5, v55
	v_add_u32_e32 v34, v32, v53
	v_add_u32_e32 v35, s5, v60
	v_sub_u32_e32 v32, s28, v34
	v_cndmask_b32_e64 v32, v32, v35, s[16:17]
	v_ashrrev_i32_e32 v33, 31, v32
	v_lshlrev_b64 v[32:33], 13, v[32:33]
	v_lshl_add_u64 v[32:33], v[40:41], 0, v[32:33]
	global_load_ushort v243, v[32:33], off
	v_xad_u32 v32, v34, -1, s28
	v_or_b32_e32 v33, 1, v35
	v_cndmask_b32_e64 v32, v32, v33, s[16:17]
	v_ashrrev_i32_e32 v33, 31, v32
	v_lshlrev_b64 v[32:33], 13, v[32:33]
	v_lshl_add_u64 v[32:33], v[40:41], 0, v[32:33]
	global_load_ushort v244, v[32:33], off
	v_sub_u32_e32 v32, s29, v34
	v_or_b32_e32 v33, 2, v35
	v_cndmask_b32_e64 v32, v32, v33, s[16:17]
	v_ashrrev_i32_e32 v33, 31, v32
	v_lshlrev_b64 v[32:33], 13, v[32:33]
	v_lshl_add_u64 v[32:33], v[40:41], 0, v[32:33]
	global_load_ushort v245, v[32:33], off
	v_sub_u32_e32 v32, s30, v34
	v_or_b32_e32 v33, 3, v35
	v_cndmask_b32_e64 v32, v32, v33, s[16:17]
	v_ashrrev_i32_e32 v33, 31, v32
	v_lshlrev_b64 v[32:33], 13, v[32:33]
	v_lshl_add_u64 v[32:33], v[40:41], 0, v[32:33]
	global_load_ushort v246, v[32:33], off
	v_sub_u32_e32 v32, s31, v34
	v_or_b32_e32 v33, 4, v35
	v_cndmask_b32_e64 v32, v32, v33, s[16:17]
	v_ashrrev_i32_e32 v33, 31, v32
	v_lshlrev_b64 v[32:33], 13, v[32:33]
	v_lshl_add_u64 v[32:33], v[40:41], 0, v[32:33]
	global_load_ushort v247, v[32:33], off
	v_sub_u32_e32 v32, s34, v34
	v_or_b32_e32 v33, 5, v35
	v_cndmask_b32_e64 v32, v32, v33, s[16:17]
	v_ashrrev_i32_e32 v33, 31, v32
	v_lshlrev_b64 v[32:33], 13, v[32:33]
	v_lshl_add_u64 v[32:33], v[40:41], 0, v[32:33]
	global_load_ushort v248, v[32:33], off
	v_sub_u32_e32 v32, s35, v34
	v_or_b32_e32 v33, 6, v35
	v_cndmask_b32_e64 v32, v32, v33, s[16:17]
	v_ashrrev_i32_e32 v33, 31, v32
	v_lshlrev_b64 v[32:33], 13, v[32:33]
	v_lshl_add_u64 v[32:33], v[40:41], 0, v[32:33]
	global_load_ushort v250, v[32:33], off
	v_sub_u32_e32 v32, s36, v34
	v_or_b32_e32 v33, 7, v35
	v_cndmask_b32_e64 v32, v32, v33, s[16:17]
	v_ashrrev_i32_e32 v33, 31, v32
	v_lshlrev_b64 v[32:33], 13, v[32:33]
	v_lshl_add_u64 v[32:33], v[40:41], 0, v[32:33]
	global_load_ushort v35, v[32:33], off

; DEV float bf2f(bf16_t b) { return __uint_as_float((unsigned)b << 16); }
; template <int PASS>
; DEV void hgrn_task(unsigned char* lds, int task, int l, const bf16_t* BZ, float* E, float* Dd, float* OF, bf16_t* YB, const float* b_lb, const float* gout) {
;     ...
;                 float P = 1.f; float ki[16], pv[16];
; #pragma unroll
;                 for (int tp = 0; tp < 16; ++tp) { const float z = bf2f(zr[tp]);
;                     const float sp = __builtin_amdgcn_rcpf(1.f + __expf(-z)), sn = __builtin_amdgcn_rcpf(1.f + __expf(z)); const float f = lb + (1.f - lb) * sp, key = (1.f - lb) * sn;
;                     P *= f; const float kiv = key * __builtin_amdgcn_rcpf(fmaxf(P, 1e-36f)); ki[tp] = kiv;
;                     pv[tp] = P; }
.LBB0_570:
	s_waitcnt lgkmcnt(0)
	v_lshlrev_b32_e32 v38, 16, v69
	v_mul_f32_e32 v39, 0xbfb8aa3b, v38
	v_mul_f32_e32 v38, 0x3fb8aa3b, v38
	v_exp_f32_e32 v38, v38
	v_lshlrev_b32_e32 v41, 16, v73
	v_exp_f32_e32 v39, v39
	s_lshl_b32 s4, s35, 6
	v_add_f32_e32 v38, 1.0, v38
	v_rcp_f32_e32 v38, v38
	v_add_f32_e32 v39, 1.0, v39
	v_rcp_f32_e32 v39, v39
	s_cmp_eq_u32 s35, 15
	v_mul_f32_e32 v40, v109, v38
	v_mul_f32_e32 v38, 0xbfb8aa3b, v41
	v_exp_f32_e32 v38, v38
	v_mul_f32_e32 v41, 0x3fb8aa3b, v41
	v_exp_f32_e32 v41, v41
	v_add_f32_e32 v38, 1.0, v38
	v_rcp_f32_e32 v38, v38
	v_add_f32_e32 v41, 1.0, v41
	v_rcp_f32_e32 v41, v41
	v_pk_fma_f32 v[38:39], v[112:113], v[38:39], v[110:111]
	s_nop 0
	v_max_f32_e32 v42, 0x3aa2425, v39
	v_rcp_f32_e32 v42, v42
	s_nop 0
	v_mul_f32_e32 v48, v40, v42
	v_mul_f32_e32 v42, v109, v41
	v_pk_mul_f32 v[40:41], v[38:39], v[38:39] op_sel:[0,1] op_sel_hi:[1,0]
	s_nop 0
	v_max_f32_e32 v38, 0x3aa2425, v40
	v_rcp_f32_e32 v38, v38
	v_lshlrev_b32_e32 v41, 16, v77
	v_mul_f32_e32 v38, v42, v38
	v_mul_f32_e32 v42, 0xbfb8aa3b, v41
	v_mul_f32_e32 v41, 0x3fb8aa3b, v41
	v_exp_f32_e32 v41, v41
	v_exp_f32_e32 v42, v42
	v_add_f32_e32 v41, 1.0, v41
	v_add_f32_e32 v42, 1.0, v42
	v_rcp_f32_e32 v41, v41
	v_rcp_f32_e32 v42, v42
	v_mul_f32_e32 v44, v109, v41
	v_lshlrev_b32_e32 v41, 16, v81
	v_fma_f32 v108, v109, v42, v105
	v_mul_f32_e32 v42, 0xbfb8aa3b, v41
	v_exp_f32_e32 v42, v42
	v_mul_f32_e32 v41, 0x3fb8aa3b, v41
	v_exp_f32_e32 v41, v41
	v_add_f32_e32 v42, 1.0, v42
	v_rcp_f32_e32 v42, v42
	v_add_f32_e32 v41, 1.0, v41
	v_rcp_f32_e32 v41, v41
	v_fma_f32 v104, v109, v42, v105
	v_lshlrev_b32_e32 v42, 16, v85
	v_mul_f32_e32 v46, v109, v41
	v_mul_f32_e32 v41, 0xbfb8aa3b, v42
	v_exp_f32_e32 v41, v41
	v_mul_f32_e32 v42, 0x3fb8aa3b, v42
	v_exp_f32_e32 v42, v42
	v_add_f32_e32 v41, 1.0, v41
	v_rcp_f32_e32 v41, v41
	v_add_f32_e32 v42, 1.0, v42
	v_rcp_f32_e32 v47, v42
	v_pk_mul_f32 v[42:43], v[108:109], v[40:41]
	s_nop 0
	v_max_f32_e32 v41, 0x3aa2425, v42
	v_rcp_f32_e32 v41, v41
	v_mul_f32_e32 v50, v109, v47
	v_mul_f32_e32 v41, v44, v41
	v_pk_mul_f32 v[44:45], v[104:105], v[42:43]
	s_nop 0
	v_max_f32_e32 v45, 0x3aa2425, v44
	v_rcp_f32_e32 v45, v45
	s_nop 0
	v_mul_f32_e32 v49, v46, v45
	v_lshlrev_b32_e32 v45, 16, v89
	v_mul_f32_e32 v46, 0xbfb8aa3b, v45
	v_exp_f32_e32 v46, v46
	v_mul_f32_e32 v45, 0x3fb8aa3b, v45
	v_exp_f32_e32 v45, v45
	v_add_f32_e32 v46, 1.0, v46
	v_rcp_f32_e32 v47, v46
	v_add_f32_e32 v45, 1.0, v45
	v_rcp_f32_e32 v51, v45
	v_mov_b32_e32 v45, v109
	v_add_f32_e32 v46, v105, v43
	v_pk_mul_f32 v[46:47], v[44:45], v[46:47]
	s_nop 0
	v_max_f32_e32 v43, 0x3aa2425, v46
	v_rcp_f32_e32 v43, v43
	v_add_f32_e32 v45, v105, v47
	v_mul_f32_e32 v47, v109, v51
	v_mul_f32_e32 v43, v50, v43
	v_mul_f32_e32 v50, v46, v45
	v_max_f32_e32 v45, 0x3aa2425, v50
	v_rcp_f32_e32 v45, v45
	s_nop 0
	v_mul_f32_e32 v45, v47, v45
	v_lshlrev_b32_e32 v47, 16, v93
	v_mul_f32_e32 v51, 0xbfb8aa3b, v47
	v_exp_f32_e32 v51, v51
	v_mul_f32_e32 v47, 0x3fb8aa3b, v47
	v_exp_f32_e32 v47, v47
	v_add_f32_e32 v51, 1.0, v51
	v_rcp_f32_e32 v51, v51
	v_add_f32_e32 v47, 1.0, v47
	v_rcp_f32_e32 v47, v47
	v_fma_f32 v51, v109, v51, v105
	v_mul_f32_e32 v52, v50, v51
	v_max_f32_e32 v51, 0x3aa2425, v52
	v_rcp_f32_e32 v51, v51
	v_mul_f32_e32 v47, v109, v47
	v_mul_f32_e32 v47, v47, v51
	v_lshlrev_b32_e32 v51, 16, v97
	v_mul_f32_e32 v53, 0xbfb8aa3b, v51
	v_exp_f32_e32 v53, v53
	v_mul_f32_e32 v51, 0x3fb8aa3b, v51
	v_exp_f32_e32 v51, v51
	v_add_f32_e32 v53, 1.0, v53
	v_rcp_f32_e32 v53, v53
	v_add_f32_e32 v51, 1.0, v51
	v_rcp_f32_e32 v51, v51
	v_fma_f32 v53, v109, v53, v105
	v_mul_f32_e32 v53, v52, v53
	v_max_f32_e32 v103, 0x3aa2425, v53
	v_rcp_f32_e32 v103, v103
	v_mul_f32_e32 v51, v109, v51
	v_mul_f32_e32 v51, v51, v103
	v_lshlrev_b32_e32 v103, 16, v101
	v_mul_f32_e32 v104, 0xbfb8aa3b, v103
	v_exp_f32_e32 v104, v104
	v_mul_f32_e32 v103, 0x3fb8aa3b, v103
	v_exp_f32_e32 v103, v103
	v_add_f32_e32 v104, 1.0, v104
	v_rcp_f32_e32 v104, v104
	v_add_f32_e32 v103, 1.0, v103
	v_rcp_f32_e32 v103, v103
	v_fma_f32 v104, v109, v104, v105
	v_mul_f32_e32 v104, v53, v104
	v_max_f32_e32 v108, 0x3aa2425, v104
	v_rcp_f32_e32 v108, v108
	v_mul_f32_e32 v103, v109, v103
	v_mul_f32_e32 v103, v103, v108
	v_lshlrev_b32_e32 v108, 16, v244
	v_mul_f32_e32 v114, 0xbfb8aa3b, v108
	v_exp_f32_e32 v114, v114
	v_mul_f32_e32 v108, 0x3fb8aa3b, v108
	v_exp_f32_e32 v108, v108
	v_add_f32_e32 v114, 1.0, v114
	v_rcp_f32_e32 v114, v114
	v_add_f32_e32 v108, 1.0, v108
	v_rcp_f32_e32 v108, v108
	v_fma_f32 v114, v109, v114, v105
	v_mul_f32_e32 v118, v104, v114
	v_max_f32_e32 v114, 0x3aa2425, v118
	v_rcp_f32_e32 v114, v114
	v_mul_f32_e32 v108, v109, v108
	v_mul_f32_e32 v119, v108, v114
	v_lshlrev_b32_e32 v108, 16, v246
	v_mul_f32_e32 v114, 0xbfb8aa3b, v108
	v_exp_f32_e32 v114, v114
	v_mul_f32_e32 v108, 0x3fb8aa3b, v108
	v_exp_f32_e32 v108, v108
	v_add_f32_e32 v114, 1.0, v114
	v_rcp_f32_e32 v114, v114
	v_add_f32_e32 v108, 1.0, v108
	v_rcp_f32_e32 v108, v108
	v_fma_f32 v114, v109, v114, v105
	v_mul_f32_e32 v120, v118, v114
	v_max_f32_e32 v114, 0x3aa2425, v120
	v_rcp_f32_e32 v114, v114
	v_mul_f32_e32 v108, v109, v108
	v_mul_f32_e32 v121, v108, v114
	v_lshlrev_b32_e32 v108, 16, v248
	v_mul_f32_e32 v114, 0xbfb8aa3b, v108
	v_exp_f32_e32 v114, v114
	v_mul_f32_e32 v108, 0x3fb8aa3b, v108
	v_exp_f32_e32 v108, v108
	v_add_f32_e32 v114, 1.0, v114
	v_rcp_f32_e32 v114, v114
	v_add_f32_e32 v108, 1.0, v108
	v_rcp_f32_e32 v108, v108
	v_fma_f32 v114, v109, v114, v105
	v_mul_f32_e32 v122, v120, v114
	v_max_f32_e32 v114, 0x3aa2425, v122
	v_rcp_f32_e32 v114, v114
	v_mul_f32_e32 v108, v109, v108
	v_mul_f32_e32 v123, v108, v114
	v_lshlrev_b32_e32 v108, 16, v251
; DEV float bf2f(bf16_t b) { return __uint_as_float((unsigned)b << 16); }
; DEV unsigned pk2(float lo, float hi) { return pg8::cvt_pk_bf16(lo, hi); }
; DEV unsigned pk2b(float lo, float hi) { const f32x2 v = {lo, hi}; const bf16x2_t b = __builtin_convertvector(v, bf16x2_t); return __builtin_bit_cast(unsigned, b); }
; template <int PASS>
; DEV void hgrn_task(unsigned char* lds, int task, int l, const bf16_t* BZ, float* E, float* Dd, float* OF, bf16_t* YB, const float* b_lb, const float* gout) {
;     ...
;                 if (PASS == 3) {
; #pragma unroll
;                     for (int tp = 0; tp < 16; ++tp) { const float qd_ = bf2f(qr[tp]) * pv[tp]; QD[(pj * 16 + tp) * QP + pc] = (bf16_t)(pk2b(qd_, 0.f) & 0xffffu); KI[(pj * 16 + tp) * QP + pc] = (bf16_t)(pk2b(ki[tp], 0.f) & 0xffffu); } }
;                 u32x4 w0, w1;
;                 w0.x = pk2(ki[0] * P, ki[1] * P); w0.y = pk2(ki[2] * P, ki[3] * P); w0.z = pk2(ki[4] * P, ki[5] * P); w0.w = pk2(ki[6] * P, ki[7] * P);
;                 w1.x = pk2(ki[8] * P, ki[9] * P); w1.y = pk2(ki[10] * P, ki[11] * P); w1.z = pk2(ki[12] * P, ki[13] * P); w1.w = pk2(ki[14] * P, ki[15] * P);
;                 *(u32x4*)(KET + (pj * 128 + pc) * 16) = w0; *(u32x4*)(KET + (pj * 128 + pc) * 16 + 8) = w1;
;                 DEC[pj * 128 + pc] = P; if (PASS == 1) dprod *= P;
;                 u32x4 vw; vw.x = vv[0] | ((unsigned)vv[1] << 16); vw.y = vv[2] | ((unsigned)vv[3] << 16); vw.z = vv[4] | ((unsigned)vv[5] << 16); vw.w = vv[6] | ((unsigned)vv[7] << 16);
;                 *(u32x4*)(VT + (pj * 64 + vn) * 16 + vsh * 8) = vw;
;             }
;             __syncthreads();
	v_mul_f32_e32 v114, 0xbfb8aa3b, v108
	v_exp_f32_e32 v114, v114
	v_mul_f32_e32 v108, 0x3fb8aa3b, v108
	v_exp_f32_e32 v108, v108
	v_add_f32_e32 v114, 1.0, v114
	v_rcp_f32_e32 v114, v114
	v_add_f32_e32 v108, 1.0, v108
	v_rcp_f32_e32 v108, v108
	v_fma_f32 v114, v109, v114, v105
	v_mul_f32_e32 v124, v122, v114
	v_max_f32_e32 v114, 0x3aa2425, v124
	v_rcp_f32_e32 v114, v114
	v_mul_f32_e32 v108, v109, v108
	v_mul_f32_e32 v125, v108, v114
	v_lshlrev_b32_e32 v108, 16, v253
	v_mul_f32_e32 v114, 0xbfb8aa3b, v108
	v_exp_f32_e32 v114, v114
	v_mul_f32_e32 v108, 0x3fb8aa3b, v108
	v_exp_f32_e32 v108, v108
	v_add_f32_e32 v114, 1.0, v114
	v_rcp_f32_e32 v114, v114
	v_add_f32_e32 v108, 1.0, v108
	v_rcp_f32_e32 v108, v108
	v_fma_f32 v114, v109, v114, v105
	v_mul_f32_e32 v115, v109, v108
	v_mul_f32_e32 v108, v124, v114
	v_max_f32_e32 v114, 0x3aa2425, v108
	v_rcp_f32_e32 v114, v114
	s_nop 0
	v_mul_f32_e32 v126, v115, v114
	v_lshlrev_b32_e32 v114, 16, v195
	v_mul_f32_e32 v115, 0xbfb8aa3b, v114
	v_exp_f32_e32 v115, v115
	v_mul_f32_e32 v114, 0x3fb8aa3b, v114
	v_exp_f32_e32 v114, v114
	v_add_f32_e32 v115, 1.0, v115
	v_rcp_f32_e32 v116, v115
	v_add_f32_e32 v114, 1.0, v114
	v_rcp_f32_e32 v115, v114
	v_fma_f32 v114, v109, v116, v105
	v_lshlrev_b32_e32 v116, 16, v197
	v_mul_f32_e32 v117, 0xbfb8aa3b, v116
	v_exp_f32_e32 v117, v117
	v_mul_f32_e32 v116, 0x3fb8aa3b, v116
	v_exp_f32_e32 v116, v116
	v_pk_mul_f32 v[114:115], v[108:109], v[114:115]
	v_add_f32_e32 v117, 1.0, v117
	v_rcp_f32_e32 v117, v117
	v_add_f32_e32 v116, 1.0, v116
	v_rcp_f32_e32 v127, v116
	v_fma_f32 v116, v109, v117, v105
	v_max_f32_e32 v117, 0x3aa2425, v114
	v_rcp_f32_e32 v117, v117
	v_mul_f32_e32 v127, v109, v127
	v_pk_mul_f32 v[116:117], v[114:115], v[116:117]
	s_nop 0
	v_max_f32_e32 v115, 0x3aa2425, v116
	v_rcp_f32_e32 v115, v115
	s_nop 0
	v_mul_f32_e32 v115, v127, v115
	v_lshlrev_b32_e32 v127, 16, v71
	v_mul_f32_e32 v39, v39, v127
	v_cvt_pk_bf16_f32 v39, v39, s0
	ds_write_b16 v214, v39
	v_cvt_pk_bf16_f32 v39, v48, s0
	ds_write_b16 v214, v39 offset:17408
	v_lshlrev_b32_e32 v39, 16, v75
	v_mul_f32_e32 v39, v40, v39
	v_cvt_pk_bf16_f32 v39, v39, s0
	ds_write_b16 v215, v39
	v_cvt_pk_bf16_f32 v39, v38, s0
	ds_write_b16 v215, v39 offset:17408
	v_lshlrev_b32_e32 v39, 16, v79
	v_mul_f32_e32 v39, v42, v39
	v_cvt_pk_bf16_f32 v39, v39, s0
	ds_write_b16 v216, v39
	v_cvt_pk_bf16_f32 v39, v41, s0
	ds_write_b16 v216, v39 offset:17408
	v_lshlrev_b32_e32 v39, 16, v83
	v_mul_f32_e32 v39, v44, v39
	v_cvt_pk_bf16_f32 v39, v39, s0
	ds_write_b16 v217, v39
	v_cvt_pk_bf16_f32 v39, v49, s0
	ds_write_b16 v217, v39 offset:17408
	v_lshlrev_b32_e32 v39, 16, v87
	v_mul_f32_e32 v39, v46, v39
	v_cvt_pk_bf16_f32 v39, v39, s0
	ds_write_b16 v218, v39
	v_cvt_pk_bf16_f32 v39, v43, s0
	ds_write_b16 v218, v39 offset:17408
	v_lshlrev_b32_e32 v39, 16, v91
	v_mul_f32_e32 v39, v50, v39
	v_cvt_pk_bf16_f32 v39, v39, s0
	ds_write_b16 v219, v39
	v_cvt_pk_bf16_f32 v39, v45, s0
	ds_write_b16 v219, v39 offset:17408
	v_lshlrev_b32_e32 v39, 16, v95
	v_mul_f32_e32 v39, v52, v39
	v_cvt_pk_bf16_f32 v39, v39, s0
	ds_write_b16 v220, v39
	v_cvt_pk_bf16_f32 v39, v47, s0
	ds_write_b16 v220, v39 offset:17408
	v_lshlrev_b32_e32 v39, 16, v99
	v_mul_f32_e32 v39, v53, v39
	v_cvt_pk_bf16_f32 v39, v39, s0
	ds_write_b16 v221, v39
	v_cvt_pk_bf16_f32 v39, v51, s0
	ds_write_b16 v221, v39 offset:17408
	v_lshlrev_b32_e32 v39, 16, v243
	v_mul_f32_e32 v39, v104, v39
	v_cvt_pk_bf16_f32 v39, v39, s0
	ds_write_b16 v222, v39
	v_cvt_pk_bf16_f32 v39, v103, s0
	ds_write_b16 v222, v39 offset:17408
	v_lshlrev_b32_e32 v39, 16, v245
	v_mul_f32_e32 v39, v118, v39
	v_cvt_pk_bf16_f32 v39, v39, s0
	ds_write_b16 v223, v39
	v_cvt_pk_bf16_f32 v39, v119, s0
	ds_write_b16 v223, v39 offset:17408
	v_lshlrev_b32_e32 v39, 16, v247
	v_mul_f32_e32 v39, v120, v39
	v_cvt_pk_bf16_f32 v39, v39, s0
	ds_write_b16 v229, v39
	v_cvt_pk_bf16_f32 v39, v121, s0
	ds_write_b16 v229, v39 offset:17408
	v_lshlrev_b32_e32 v39, 16, v250
	v_mul_f32_e32 v39, v122, v39
	v_cvt_pk_bf16_f32 v39, v39, s0
	ds_write_b16 v230, v39
	v_cvt_pk_bf16_f32 v39, v123, s0
	ds_write_b16 v230, v39 offset:17408
	v_lshlrev_b32_e32 v39, 16, v252
	v_mul_f32_e32 v39, v124, v39
	v_cvt_pk_bf16_f32 v39, v39, s0
	ds_write_b16 v231, v39
	v_cvt_pk_bf16_f32 v39, v125, s0
	ds_write_b16 v231, v39 offset:17408
	v_lshlrev_b32_e32 v39, 16, v194
	v_mul_f32_e32 v39, v108, v39
	v_cvt_pk_bf16_f32 v39, v39, s0
	ds_write_b16 v232, v39
	v_cvt_pk_bf16_f32 v39, v126, s0
	ds_write_b16 v232, v39 offset:17408
	v_lshlrev_b32_e32 v39, 16, v196
	v_mul_f32_e32 v39, v114, v39
	v_cvt_pk_bf16_f32 v39, v39, s0
	ds_write_b16 v233, v39
	v_cvt_pk_bf16_f32 v39, v117, s0
	ds_write_b16 v233, v39 offset:17408
	v_lshlrev_b32_e32 v39, 16, v198
	v_mul_f32_e32 v39, v116, v39
	v_cvt_pk_bf16_f32 v39, v39, s0
	ds_write_b16 v234, v39
	v_cvt_pk_bf16_f32 v39, v115, s0
	ds_write_b16 v234, v39 offset:17408
	v_mul_f32_e32 v39, v48, v116
	v_mul_f32_e32 v38, v38, v116
	v_cvt_pk_bf16_f32 v38, v39, v38
	v_mul_f32_e32 v39, v41, v116
	v_mul_f32_e32 v40, v49, v116
	v_cvt_pk_bf16_f32 v39, v39, v40
	v_mul_f32_e32 v40, v43, v116
	v_mul_f32_e32 v41, v45, v116
	v_cvt_pk_bf16_f32 v40, v40, v41
	v_mul_f32_e32 v41, v47, v116
	v_mul_f32_e32 v42, v51, v116
	v_cvt_pk_bf16_f32 v41, v41, v42
	v_mul_f32_e32 v42, v103, v116
	v_mul_f32_e32 v43, v119, v116
	v_cvt_pk_bf16_f32 v42, v42, v43
	v_mul_f32_e32 v43, v121, v116
	v_mul_f32_e32 v44, v123, v116
	v_cvt_pk_bf16_f32 v43, v43, v44
	v_mul_f32_e32 v44, v125, v116
	v_mul_f32_e32 v45, v116, v126
	v_cvt_pk_bf16_f32 v44, v44, v45
	v_mul_f32_e32 v45, v116, v117
	v_mul_f32_e32 v46, v116, v115
	v_cvt_pk_bf16_f32 v45, v45, v46
	ds_write_b128 v144, v[38:41] offset:34816
	ds_write_b128 v144, v[42:45] offset:34832
	ds_write_b32 v242, v116 offset:59392
	ds_write_b128 v152, v[34:37] offset:51200
	s_waitcnt lgkmcnt(0)
	s_barrier
; #define HLOADS(g0_) do { _Pragma("unroll") for (int tp = 0; tp < 16; ++tp) { const size_t rb = (size_t)HROW((g0_) + pj * 16 + tp) * 4096; zr[tp] = zb[rb]; if (PASS == 3) qr[tp] = qb[rb]; } \
;             _Pragma("unroll") for (int s8 = 0; s8 < 8; ++s8) vv[s8] = vb[(size_t)HROW((g0_) + pj * 16 + vsh * 8 + s8) * 4096]; } while (0)
; template <int PASS>
; DEV void hgrn_task(unsigned char* lds, int task, int l, const bf16_t* BZ, float* E, float* Dd, float* OF, bf16_t* YB, const float* b_lb, const float* gout) {
;     ...
;             if (stg + 1 < 16) HLOADS(g0 + 64);
	s_cbranch_scc1 .LBB0_572
	v_add_u32_e32 v38, s4, v146
	v_add_u32_e32 v39, s4, v153
	v_sub_u32_e32 v34, s75, v38
	v_cndmask_b32_e64 v34, v34, v39, s[28:29]
	v_ashrrev_i32_e32 v35, 31, v34
	v_lshlrev_b64 v[34:35], 13, v[34:35]
	v_lshl_add_u64 v[36:37], v[106:107], 0, v[34:35]
	v_lshl_add_u64 v[34:35], v[54:55], 0, v[34:35]
	global_load_ushort v69, v[36:37], off
	global_load_ushort v71, v[34:35], off
	v_xad_u32 v34, v38, -1, s75
	v_or_b32_e32 v35, 1, v39
	v_cndmask_b32_e64 v34, v34, v35, s[28:29]
	v_ashrrev_i32_e32 v35, 31, v34
	v_lshlrev_b64 v[34:35], 13, v[34:35]
	v_lshl_add_u64 v[36:37], v[106:107], 0, v[34:35]
	v_lshl_add_u64 v[34:35], v[54:55], 0, v[34:35]
	global_load_ushort v73, v[36:37], off
	global_load_ushort v75, v[34:35], off
	v_sub_u32_e32 v34, s84, v38
	v_or_b32_e32 v35, 2, v39
	v_cndmask_b32_e64 v34, v34, v35, s[28:29]
	v_ashrrev_i32_e32 v35, 31, v34
	v_lshlrev_b64 v[34:35], 13, v[34:35]
	v_lshl_add_u64 v[36:37], v[106:107], 0, v[34:35]
	v_lshl_add_u64 v[34:35], v[54:55], 0, v[34:35]
	global_load_ushort v77, v[36:37], off
	global_load_ushort v79, v[34:35], off
	v_sub_u32_e32 v34, s85, v38
	v_or_b32_e32 v35, 3, v39
	v_cndmask_b32_e64 v34, v34, v35, s[28:29]
	v_ashrrev_i32_e32 v35, 31, v34
	v_lshlrev_b64 v[34:35], 13, v[34:35]
	v_lshl_add_u64 v[36:37], v[106:107], 0, v[34:35]
	v_lshl_add_u64 v[34:35], v[54:55], 0, v[34:35]
	global_load_ushort v81, v[36:37], off
	global_load_ushort v83, v[34:35], off
	v_sub_u32_e32 v34, s88, v38
	v_or_b32_e32 v35, 4, v39
	v_cndmask_b32_e64 v34, v34, v35, s[28:29]
	v_ashrrev_i32_e32 v35, 31, v34
	v_lshlrev_b64 v[34:35], 13, v[34:35]
	v_lshl_add_u64 v[36:37], v[106:107], 0, v[34:35]
	v_lshl_add_u64 v[34:35], v[54:55], 0, v[34:35]
	global_load_ushort v85, v[36:37], off
	global_load_ushort v87, v[34:35], off
	v_sub_u32_e32 v34, s89, v38
	v_or_b32_e32 v35, 5, v39
	v_cndmask_b32_e64 v34, v34, v35, s[28:29]
	v_ashrrev_i32_e32 v35, 31, v34
	v_lshlrev_b64 v[34:35], 13, v[34:35]
	v_lshl_add_u64 v[36:37], v[106:107], 0, v[34:35]
	v_lshl_add_u64 v[34:35], v[54:55], 0, v[34:35]
	global_load_ushort v89, v[36:37], off
	global_load_ushort v91, v[34:35], off
	v_sub_u32_e32 v34, s90, v38
	v_or_b32_e32 v35, 6, v39
	v_cndmask_b32_e64 v34, v34, v35, s[28:29]
	v_ashrrev_i32_e32 v35, 31, v34
	v_lshlrev_b64 v[34:35], 13, v[34:35]
	v_lshl_add_u64 v[36:37], v[106:107], 0, v[34:35]
	v_lshl_add_u64 v[34:35], v[54:55], 0, v[34:35]
	global_load_ushort v93, v[36:37], off
	global_load_ushort v95, v[34:35], off
	v_sub_u32_e32 v34, s91, v38
	v_or_b32_e32 v35, 7, v39
	v_cndmask_b32_e64 v34, v34, v35, s[28:29]
	v_ashrrev_i32_e32 v35, 31, v34
	v_lshlrev_b64 v[34:35], 13, v[34:35]
	v_lshl_add_u64 v[36:37], v[106:107], 0, v[34:35]
	v_lshl_add_u64 v[34:35], v[54:55], 0, v[34:35]
	global_load_ushort v97, v[36:37], off
	global_load_ushort v99, v[34:35], off
	v_sub_u32_e32 v34, s92, v38
	v_or_b32_e32 v35, 8, v39
	v_cndmask_b32_e64 v34, v34, v35, s[28:29]
	v_ashrrev_i32_e32 v35, 31, v34
	v_lshlrev_b64 v[34:35], 13, v[34:35]
	v_lshl_add_u64 v[36:37], v[106:107], 0, v[34:35]
	v_lshl_add_u64 v[34:35], v[54:55], 0, v[34:35]
	global_load_ushort v101, v[36:37], off
	global_load_ushort v243, v[34:35], off
	v_sub_u32_e32 v34, s93, v38
	v_or_b32_e32 v35, 9, v39
	v_cndmask_b32_e64 v34, v34, v35, s[28:29]
	v_ashrrev_i32_e32 v35, 31, v34
	v_lshlrev_b64 v[34:35], 13, v[34:35]
	v_lshl_add_u64 v[36:37], v[106:107], 0, v[34:35]
	v_lshl_add_u64 v[34:35], v[54:55], 0, v[34:35]
	global_load_ushort v244, v[36:37], off
	global_load_ushort v245, v[34:35], off
	v_sub_u32_e32 v34, s94, v38
	v_or_b32_e32 v35, 10, v39
	v_cndmask_b32_e64 v34, v34, v35, s[28:29]
	v_ashrrev_i32_e32 v35, 31, v34
	v_lshlrev_b64 v[34:35], 13, v[34:35]
	v_lshl_add_u64 v[36:37], v[106:107], 0, v[34:35]
	v_lshl_add_u64 v[34:35], v[54:55], 0, v[34:35]
	global_load_ushort v246, v[36:37], off
	global_load_ushort v247, v[34:35], off
; #define HLOADS(g0_) do { _Pragma("unroll") for (int tp = 0; tp < 16; ++tp) { const size_t rb = (size_t)HROW((g0_) + pj * 16 + tp) * 4096; zr[tp] = zb[rb]; if (PASS == 3) qr[tp] = qb[rb]; } \
;             _Pragma("unroll") for (int s8 = 0; s8 < 8; ++s8) vv[s8] = vb[(size_t)HROW((g0_) + pj * 16 + vsh * 8 + s8) * 4096]; } while (0)
; template <int PASS>
; DEV void hgrn_task(unsigned char* lds, int task, int l, const bf16_t* BZ, float* E, float* Dd, float* OF, bf16_t* YB, const float* b_lb, const float* gout) {
;     ...
;             if (stg + 1 < 16) HLOADS(g0 + 64);
	v_sub_u32_e32 v34, s95, v38
	v_or_b32_e32 v35, 11, v39
	v_cndmask_b32_e64 v34, v34, v35, s[28:29]
	v_ashrrev_i32_e32 v35, 31, v34
	v_lshlrev_b64 v[34:35], 13, v[34:35]
	v_lshl_add_u64 v[36:37], v[106:107], 0, v[34:35]
	v_lshl_add_u64 v[34:35], v[54:55], 0, v[34:35]
	global_load_ushort v248, v[36:37], off
	global_load_ushort v250, v[34:35], off
	v_sub_u32_e32 v34, s96, v38
	v_or_b32_e32 v35, 12, v39
	v_cndmask_b32_e64 v34, v34, v35, s[28:29]
	v_ashrrev_i32_e32 v35, 31, v34
	v_lshlrev_b64 v[34:35], 13, v[34:35]
	v_lshl_add_u64 v[36:37], v[106:107], 0, v[34:35]
	v_lshl_add_u64 v[34:35], v[54:55], 0, v[34:35]
	global_load_ushort v251, v[36:37], off
	global_load_ushort v252, v[34:35], off
	v_sub_u32_e32 v34, s97, v38
	v_or_b32_e32 v35, 13, v39
	v_cndmask_b32_e64 v34, v34, v35, s[28:29]
	v_ashrrev_i32_e32 v35, 31, v34
	v_lshlrev_b64 v[34:35], 13, v[34:35]
	v_lshl_add_u64 v[36:37], v[106:107], 0, v[34:35]
	v_lshl_add_u64 v[34:35], v[54:55], 0, v[34:35]
	global_load_ushort v253, v[36:37], off
	global_load_ushort v194, v[34:35], off
	v_sub_u32_e32 v34, s87, v38
	v_or_b32_e32 v35, 14, v39
	v_cndmask_b32_e64 v34, v34, v35, s[28:29]
	v_ashrrev_i32_e32 v35, 31, v34
	v_lshlrev_b64 v[34:35], 13, v[34:35]
	v_lshl_add_u64 v[36:37], v[106:107], 0, v[34:35]
	v_lshl_add_u64 v[34:35], v[54:55], 0, v[34:35]
	global_load_ushort v195, v[36:37], off
	global_load_ushort v196, v[34:35], off
	v_sub_u32_e32 v34, s48, v38
	v_or_b32_e32 v35, 15, v39
	v_cndmask_b32_e64 v34, v34, v35, s[28:29]
	v_ashrrev_i32_e32 v35, 31, v34
	v_lshlrev_b64 v[34:35], 13, v[34:35]
	v_lshl_add_u64 v[36:37], v[106:107], 0, v[34:35]
	global_load_ushort v197, v[36:37], off
	v_or_b32_e32 v36, s4, v147
	v_add_u32_e32 v38, v36, v146
	v_add_u32_e32 v39, s4, v155
	v_sub_u32_e32 v36, s75, v38
	v_cndmask_b32_e64 v36, v36, v39, s[28:29]
	v_ashrrev_i32_e32 v37, 31, v36
	v_lshlrev_b64 v[36:37], 13, v[36:37]
	v_lshl_add_u64 v[36:37], v[56:57], 0, v[36:37]
	global_load_ushort v53, v[36:37], off
	v_xad_u32 v36, v38, -1, s75
	v_or_b32_e32 v37, 1, v39
	v_cndmask_b32_e64 v36, v36, v37, s[28:29]
	v_ashrrev_i32_e32 v37, 31, v36
	v_lshlrev_b64 v[36:37], 13, v[36:37]
	v_lshl_add_u64 v[36:37], v[56:57], 0, v[36:37]
	global_load_ushort v103, v[36:37], off
	v_sub_u32_e32 v36, s84, v38
	v_or_b32_e32 v37, 2, v39
	v_cndmask_b32_e64 v36, v36, v37, s[28:29]
	v_ashrrev_i32_e32 v37, 31, v36
	v_lshlrev_b64 v[36:37], 13, v[36:37]
	v_lshl_add_u64 v[36:37], v[56:57], 0, v[36:37]
	global_load_ushort v104, v[36:37], off
	v_sub_u32_e32 v36, s85, v38
	v_or_b32_e32 v37, 3, v39
	v_cndmask_b32_e64 v36, v36, v37, s[28:29]
	v_ashrrev_i32_e32 v37, 31, v36
	v_lshlrev_b64 v[36:37], 13, v[36:37]
	v_lshl_add_u64 v[36:37], v[56:57], 0, v[36:37]
	global_load_ushort v108, v[36:37], off
	v_sub_u32_e32 v36, s88, v38
	v_or_b32_e32 v37, 4, v39
	v_cndmask_b32_e64 v36, v36, v37, s[28:29]
	v_ashrrev_i32_e32 v37, 31, v36
	v_lshlrev_b64 v[36:37], 13, v[36:37]
	v_lshl_add_u64 v[36:37], v[56:57], 0, v[36:37]
	global_load_ushort v142, v[36:37], off
	v_sub_u32_e32 v36, s89, v38
	v_or_b32_e32 v37, 5, v39
	v_cndmask_b32_e64 v36, v36, v37, s[28:29]
	v_ashrrev_i32_e32 v37, 31, v36
	v_lshlrev_b64 v[36:37], 13, v[36:37]
	v_lshl_add_u64 v[36:37], v[56:57], 0, v[36:37]
	global_load_ushort v143, v[36:37], off
	v_sub_u32_e32 v36, s90, v38
	v_or_b32_e32 v37, 6, v39
	v_cndmask_b32_e64 v36, v36, v37, s[28:29]
	v_ashrrev_i32_e32 v37, 31, v36
	v_lshlrev_b64 v[36:37], 13, v[36:37]
	v_lshl_add_u64 v[36:37], v[56:57], 0, v[36:37]
	global_load_ushort v200, v[36:37], off
	v_sub_u32_e32 v36, s91, v38
	v_or_b32_e32 v37, 7, v39
	v_cndmask_b32_e64 v36, v36, v37, s[28:29]
	v_ashrrev_i32_e32 v37, 31, v36
	v_lshlrev_b64 v[36:37], 13, v[36:37]
	v_lshl_add_u64 v[36:37], v[56:57], 0, v[36:37]
	v_lshl_add_u64 v[34:35], v[54:55], 0, v[34:35]
	global_load_ushort v201, v[36:37], off
	s_nop 0
	global_load_ushort v198, v[34:35], off

; template <int PASS>
; DEV void hgrn_task(unsigned char* lds, int task, int l, const bf16_t* BZ, float* E, float* Dd, float* OF, bf16_t* YB, const float* b_lb, const float* gout) {
;     ...
;                 for (int j = 0; j < 4; ++j) {
;                     const bf16_t* QDj = QD + j * 16 * QP; const bf16_t* KIj = KI + j * 16 * QP; const bf16_t* KETj = KET + j * 128 * 16; const bf16_t* VTj = VT + j * 64 * 16; const float* DECj = DEC + j * 128;
;                     const s16x4 vf = *(const s16x4*)(VTj + (16 * nt + fr) * 16 + 4 * fq);
;                     if (PASS == 3) {
;                         bf16x8 qd[4]; f32x4 sc = {0.f, 0.f, 0.f, 0.f};
; #pragma unroll
;                         for (int kk = 0; kk < 4; ++kk) { const s16x4 a0 = *(const s16x4*)(QDj + fr * QP + 32 * kk + 4 * fq), a1 = *(const s16x4*)(QDj + fr * QP + 32 * kk + 16 + 4 * fq);
;                             qd[kk] = (bf16x8){a0[0], a0[1], a0[2], a0[3], a1[0], a1[1], a1[2], a1[3]};
;                             const s16x4 b0 = *(const s16x4*)(KIj + fr * QP + 32 * kk + 4 * fq), b1 = *(const s16x4*)(KIj + fr * QP + 32 * kk + 16 + 4 * fq);
;                             const bf16x8 kf = {b0[0], b0[1], b0[2], b0[3], b1[0], b1[1], b1[2], b1[3]};
;                             sc = __builtin_amdgcn_mfma_f32_16x16x32_bf16(kf, qd[kk], sc, 0, 0, 0); asm volatile("" :: "v"(kf), "v"(qd[kk])); }
; #pragma unroll
;                         for (int i = 0; i < 4; ++i) if (4 * fq + i > fr) sc[i] = 0.f;
;                         u32x2 sw; sw.x = pk2b(sc[0], sc[1]); sw.y = pk2b(sc[2], sc[3]);
;                         const s16x4 swv = __builtin_bit_cast(s16x4, sw);
;                         f32x4 z4 = {0.f, 0.f, 0.f, 0.f}; asm volatile("" : "+v"(z4));
;                         const bf16x8 sw8 = {swv[0], swv[1], swv[2], swv[3], 0, 0, 0, 0}; const bf16x8 vf8 = {vf[0], vf[1], vf[2], vf[3], 0, 0, 0, 0};
;                         f32x4 oacc = __builtin_amdgcn_mfma_f32_16x16x32_bf16(sw8, vf8, z4, 0, 0, 0); asm volatile("" :: "v"(swv), "v"(vf));
; #pragma unroll
;                         for (int kk = 0; kk < 4; ++kk) { u32x4 sb; sb.x = pk2b(st[2 * kk][0], st[2 * kk][1]); sb.y = pk2b(st[2 * kk][2], st[2 * kk][3]); sb.z = pk2b(st[2 * kk + 1][0], st[2 * kk + 1][1]); sb.w = pk2b(st[2 * kk + 1][2], st[2 * kk + 1][3]);
.LBB0_574:
	v_add_u32_e32 v40, 0, v42
	v_add_u32_e32 v41, 0x4000, v40
	ds_read2_b64 v[114:117], v41 offset0:128 offset1:132
	ds_read2_b64 v[48:51], v40 offset1:4
	v_add_u32_e32 v38, 0, v43
	ds_read_b64 v[38:39], v38
	s_waitcnt lgkmcnt(0)
	v_mov_b32_e32 v129, v128
	v_mov_b32_e32 v126, v128
	v_mov_b32_e32 v127, v128
	s_mov_b64 s[6:7], src_shared_base
	v_mfma_f32_16x16x32_bf16 v[118:121], v[114:117], v[48:51], 0
	ds_read2_b64 v[114:117], v40 offset0:8 offset1:12
	ds_read2_b64 v[122:125], v41 offset0:136 offset1:140
	s_add_i32 s5, s5, -1
	v_add_u32_e32 v43, 0x800, v43
	v_add_u32_e32 v42, 0x1100, v42
	s_waitcnt lgkmcnt(0)
	v_mfma_f32_16x16x32_bf16 v[118:121], v[122:125], v[114:117], v[118:121]
	ds_read2_b64 v[122:125], v40 offset0:16 offset1:20
	ds_read2_b64 v[130:133], v41 offset0:144 offset1:148
	s_cmp_lg_u32 s5, 0
	s_waitcnt lgkmcnt(0)
	v_mfma_f32_16x16x32_bf16 v[118:121], v[130:133], v[122:125], v[118:121]
	ds_read2_b64 v[130:133], v40 offset0:24 offset1:28
	ds_read2_b64 v[134:137], v41 offset0:152 offset1:156
	v_mov_b32_e32 v40, s67
	s_waitcnt lgkmcnt(0)
	v_mfma_f32_16x16x32_bf16 v[118:121], v[134:137], v[130:133], v[118:121]
	v_mov_b64_e32 v[136:137], v[128:129]
	v_mov_b64_e32 v[134:135], v[126:127]
	s_nop 5
	v_cndmask_b32_e64 v40, v118, v40, s[8:9]
	v_cndmask_b32_e64 v40, v40, v118, s[10:11]
	v_cndmask_b32_e64 v41, 0, v119, s[10:11]
	v_cndmask_b32_e64 v47, v120, 0, s[12:13]
	v_cndmask_b32_e64 v52, v121, 0, s[14:15]
	v_cvt_pk_bf16_f32 v118, v40, v41
	v_cvt_pk_bf16_f32 v119, v47, v52
	v_mov_b32_e32 v120, v128
	v_mov_b32_e32 v121, v128
	v_mov_b32_e32 v40, v128
	v_mov_b32_e32 v41, v128
	v_add_u32_e32 v47, 0, v44
	v_add_u32_e32 v52, 0, v45
	v_mfma_f32_16x16x32_bf16 v[134:137], v[118:121], v[38:41], v[134:137]
	v_cvt_pk_bf16_f32 v118, v2, v3
	v_cvt_pk_bf16_f32 v119, v4, v5
	v_cvt_pk_bf16_f32 v120, v6, v7
	v_cvt_pk_bf16_f32 v121, v8, v9
	v_add_u32_e32 v45, 0x1000, v45
	v_add_u32_e32 v44, 0x1000, v44
	v_mfma_f32_16x16x32_bf16 v[134:137], v[48:51], v[118:121], v[134:137]
	v_cvt_pk_bf16_f32 v48, v10, v11
	v_cvt_pk_bf16_f32 v49, v12, v13
	v_cvt_pk_bf16_f32 v50, v14, v15
	v_cvt_pk_bf16_f32 v51, v16, v17
	s_nop 1
	v_mfma_f32_16x16x32_bf16 v[118:121], v[114:117], v[48:51], v[134:137]
	v_cvt_pk_bf16_f32 v48, v18, v19
	v_cvt_pk_bf16_f32 v49, v20, v21
	v_cvt_pk_bf16_f32 v50, v22, v23
	v_cvt_pk_bf16_f32 v51, v24, v25
	s_nop 1
	v_mfma_f32_16x16x32_bf16 v[114:117], v[122:125], v[48:51], v[118:121]
	v_cvt_pk_bf16_f32 v48, v26, v27
	v_cvt_pk_bf16_f32 v49, v28, v29
	v_cvt_pk_bf16_f32 v50, v30, v31
	v_cvt_pk_bf16_f32 v51, v32, v33
	s_nop 1
	v_mfma_f32_16x16x32_bf16 v[114:117], v[130:133], v[48:51], v[114:117]
	s_nop 7
	ds_write_b32 v47, v114 offset:61440
	ds_write_b32 v47, v115 offset:61696
	ds_write_b32 v47, v116 offset:61952
	ds_write_b32 v47, v117 offset:62208
	v_add_u32_e32 v47, 0, v46
	ds_read_b128 v[48:51], v47
	ds_read2st64_b64 v[114:117], v52 offset1:1
	v_add_u32_e32 v46, 0x200, v46
	s_waitcnt lgkmcnt(0)
	v_pk_mul_f32 v[4:5], v[4:5], v[50:51]
	v_mov_b32_e32 v126, v114
	v_mov_b32_e32 v127, v115
	v_pk_mul_f32 v[2:3], v[2:3], v[48:49]
	ds_read_b128 v[48:51], v47 offset:64
	s_waitcnt lgkmcnt(0)
	v_pk_mul_f32 v[8:9], v[8:9], v[50:51]
	v_mfma_f32_16x16x32_bf16 v[2:5], v[126:129], v[38:41], v[2:5]
	v_mov_b32_e32 v126, v116
	v_mov_b32_e32 v127, v117
	v_pk_mul_f32 v[6:7], v[6:7], v[48:49]
	ds_read_b128 v[48:51], v47 offset:128
	ds_read2st64_b64 v[114:117], v52 offset0:2 offset1:3
	v_mfma_f32_16x16x32_bf16 v[6:9], v[126:129], v[38:41], v[6:9]
	s_waitcnt lgkmcnt(1)
	v_pk_mul_f32 v[12:13], v[12:13], v[50:51]
	s_waitcnt lgkmcnt(0)
	v_mov_b32_e32 v126, v114
	v_mov_b32_e32 v127, v115
	v_pk_mul_f32 v[10:11], v[10:11], v[48:49]
	ds_read_b128 v[48:51], v47 offset:192
	s_waitcnt lgkmcnt(0)
	v_pk_mul_f32 v[16:17], v[16:17], v[50:51]
	v_mfma_f32_16x16x32_bf16 v[10:13], v[126:129], v[38:41], v[10:13]
	v_mov_b32_e32 v126, v116
	v_mov_b32_e32 v127, v117
	v_pk_mul_f32 v[14:15], v[14:15], v[48:49]
	ds_read_b128 v[48:51], v47 offset:256
	ds_read2st64_b64 v[114:117], v52 offset0:4 offset1:5
	v_mfma_f32_16x16x32_bf16 v[14:17], v[126:129], v[38:41], v[14:17]
	s_waitcnt lgkmcnt(1)
	v_pk_mul_f32 v[20:21], v[20:21], v[50:51]
	s_waitcnt lgkmcnt(0)
	v_mov_b32_e32 v126, v114
	v_mov_b32_e32 v127, v115
	v_pk_mul_f32 v[18:19], v[18:19], v[48:49]
	ds_read_b128 v[48:51], v47 offset:320
	s_waitcnt lgkmcnt(0)
	v_pk_mul_f32 v[24:25], v[24:25], v[50:51]
	v_mfma_f32_16x16x32_bf16 v[18:21], v[126:129], v[38:41], v[18:21]
	v_mov_b32_e32 v126, v116
	v_mov_b32_e32 v127, v117
	v_pk_mul_f32 v[22:23], v[22:23], v[48:49]
	ds_read_b128 v[48:51], v47 offset:384
	ds_read2st64_b64 v[114:117], v52 offset0:6 offset1:7
	v_mfma_f32_16x16x32_bf16 v[22:25], v[126:129], v[38:41], v[22:25]
	s_waitcnt lgkmcnt(1)
	v_pk_mul_f32 v[28:29], v[28:29], v[50:51]
	s_waitcnt lgkmcnt(0)
	v_mov_b32_e32 v126, v114
	v_mov_b32_e32 v127, v115
	v_pk_mul_f32 v[26:27], v[26:27], v[48:49]
	ds_read_b128 v[48:51], v47 offset:448
	s_waitcnt lgkmcnt(0)
	v_pk_mul_f32 v[32:33], v[32:33], v[50:51]
	v_mfma_f32_16x16x32_bf16 v[26:29], v[126:129], v[38:41], v[26:29]
	v_mov_b32_e32 v126, v116
	v_mov_b32_e32 v127, v117
	v_pk_mul_f32 v[30:31], v[30:31], v[48:49]
	s_nop 1
	v_mfma_f32_16x16x32_bf16 v[30:33], v[126:129], v[38:41], v[30:33]
	s_cbranch_scc1 .LBB0_574
.LBB0_575:
	s_waitcnt vmcnt(0)
	v_lshl_or_b32 v34, v103, 16, v53
	v_lshl_or_b32 v35, v108, 16, v104
	v_lshl_or_b32 v36, v143, 16, v142
	v_lshl_or_b32 v37, v201, 16, v200
	v_subrev_u32_e32 v38, s4, v235
	v_add_u32_e32 v39, s4, v149
	s_barrier
	v_cndmask_b32_e64 v46, v38, v39, s[28:29]
	ds_read_b128 v[38:41], v249 offset:61440
	ds_read_b128 v[42:45], v249 offset:61456
	v_ashrrev_i32_e32 v47, 31, v46
	v_lshlrev_b64 v[48:49], 11, v[46:47]
	v_lshl_add_u64 v[114:115], v[58:59], 0, v[48:49]
	s_mov_b64 s[4:5], -1
	s_and_b64 vcc, exec, s[30:31]
	s_cbranch_vccnz .LBB0_577
	s_andn2_b64 vcc, exec, s[4:5]
	s_cbranch_vccnz .LBB0_569
	s_branch .LBB0_578

; #define PG8_LAS __attribute__((address_space(3)))
; DEV unsigned pk2(float lo, float hi) { return pg8::cvt_pk_bf16(lo, hi); }
; DEV void mla_unit(PG8_LAS unsigned char* lds, const bf16_t* Q, const bf16_t* K, const bf16_t* VT, bf16_t* O) {
;     ...
;             float rsum = 0.f;
; #pragma unroll
;             for (int r = 0; r < 16; ++r) { p0[r] = __builtin_amdgcn_exp2f(p0[r]); p1[r] = __builtin_amdgcn_exp2f(p1[r]); rsum += p0[r] + p1[r]; }
;             lrun[sb] += rsum;
; #pragma unroll
;             for (int ks = 0; ks < 4; ++ks) { u32x4 w;
;                 if (ks < 2) { w.x = pk2(p0[8 * ks + 0], p0[8 * ks + 1]); w.y = pk2(p0[8 * ks + 2], p0[8 * ks + 3]); w.z = pk2(p0[8 * ks + 4], p0[8 * ks + 5]); w.w = pk2(p0[8 * ks + 6], p0[8 * ks + 7]); }
;                 else { const int k2 = ks - 2; w.x = pk2(p1[8 * k2 + 0], p1[8 * k2 + 1]); w.y = pk2(p1[8 * k2 + 2], p1[8 * k2 + 3]); w.z = pk2(p1[8 * k2 + 4], p1[8 * k2 + 5]); w.w = pk2(p1[8 * k2 + 6], p1[8 * k2 + 7]); }
;                 pb[sb][ks] = __builtin_bit_cast(bf16x8, w); }
;         }
; #pragma unroll
;         for (int db = 0; db < 2; ++db)
; #pragma unroll
;             for (int ks = 0; ks < 4; ++ks) {
;                 const bf16x8 vf = *(PG8_LAS const bf16x8*)(Kb + vfo + db * 32 * 144 + ks * 32);
;                 o[0][db] = __builtin_amdgcn_mfma_f32_32x32x16_bf16(vf, pb[0][ks], o[0][db], 0, 0, 0);
;                 o[1][db] = __builtin_amdgcn_mfma_f32_32x32x16_bf16(vf, pb[1][ks], o[1][db], 0, 0, 0);
;             }
;         __syncthreads();
.Lmla_back1:
	v_exp_f32_e32 v178, v178
	v_exp_f32_e32 v179, v179
	v_exp_f32_e32 v180, v180
	v_add_f32_e32 v225, v178, v179
	v_cvt_pk_bf16_f32 v178, v178, v179
	s_waitcnt lgkmcnt(5)
	v_mfma_f32_32x32x16_bf16 v[48:63], v[120:123], v[100:103], v[48:63]
	v_exp_f32_e32 v181, v181
	v_exp_f32_e32 v182, v182
	v_add_f32_e32 v229, v180, v181
	v_cvt_pk_bf16_f32 v179, v180, v181
	v_exp_f32_e32 v183, v183
	s_waitcnt lgkmcnt(4)
	v_mfma_f32_32x32x16_bf16 v[32:47], v[124:127], v[100:103], v[32:47]
	v_exp_f32_e32 v184, v184
	v_add_f32_e32 v204, v182, v183
	v_cvt_pk_bf16_f32 v180, v182, v183
	v_exp_f32_e32 v185, v185
	v_exp_f32_e32 v186, v186
	s_waitcnt lgkmcnt(3)
	v_mfma_f32_32x32x16_bf16 v[48:63], v[196:199], v[112:115], v[48:63]
	v_add_f32_e32 v205, v184, v185
	v_cvt_pk_bf16_f32 v181, v184, v185
	v_exp_f32_e32 v187, v187
	v_add_f32_e32 v225, v225, v186
	v_exp_f32_e32 v188, v188
	v_add_f32_e32 v229, v229, v187
	s_waitcnt lgkmcnt(2)
	v_mfma_f32_32x32x16_bf16 v[32:47], v[200:203], v[112:115], v[32:47]
	v_cvt_pk_bf16_f32 v182, v186, v187
	v_exp_f32_e32 v189, v189
	v_add_f32_e32 v204, v204, v188
	v_exp_f32_e32 v190, v190
	v_add_f32_e32 v205, v205, v189
	s_waitcnt lgkmcnt(1)
	v_mfma_f32_32x32x16_bf16 v[48:63], v[246:249], v[116:119], v[48:63]
	v_cvt_pk_bf16_f32 v183, v188, v189
	v_exp_f32_e32 v191, v191
	v_add_f32_e32 v225, v225, v190
	v_exp_f32_e32 v192, v192
	v_add_f32_e32 v229, v229, v191
	s_waitcnt lgkmcnt(0)
	v_mfma_f32_32x32x16_bf16 v[32:47], v[250:253], v[116:119], v[32:47]
	v_cvt_pk_bf16_f32 v184, v190, v191
	v_exp_f32_e32 v193, v193
	v_add_f32_e32 v204, v204, v192
	v_exp_f32_e32 v230, v230
	v_add_f32_e32 v205, v205, v193
	v_cvt_pk_bf16_f32 v185, v192, v193
	s_waitcnt vmcnt(0)
	s_barrier
	s_xor_b32 s21, s21, 0x5800
	v_add_u32_e32 v222, s21, v194
	v_mfma_f32_32x32x16_bf16 v[16:31], v[104:107], v[178:181], v[16:31]
	v_exp_f32_e32 v231, v231
	v_add_f32_e32 v225, v225, v230
	v_exp_f32_e32 v232, v232
	v_add_f32_e32 v229, v229, v231
	v_cvt_pk_bf16_f32 v230, v230, v231
	v_mfma_f32_32x32x16_bf16 v[0:15], v[108:111], v[178:181], v[0:15]
	ds_read_b128 v[186:189], v222
	ds_read_b128 v[190:193], v222 offset:6656
	v_exp_f32_e32 v233, v233
	v_add_f32_e32 v204, v204, v232
	v_exp_f32_e32 v234, v234
	v_add_f32_e32 v205, v205, v233
	v_cvt_pk_bf16_f32 v231, v232, v233
	v_mfma_f32_32x32x16_bf16 v[16:31], v[120:123], v[182:185], v[16:31]
	v_exp_f32_e32 v235, v235
	v_add_f32_e32 v225, v225, v234
	v_exp_f32_e32 v236, v236
	v_add_f32_e32 v229, v229, v235
	v_cvt_pk_bf16_f32 v232, v234, v235
	v_mfma_f32_32x32x16_bf16 v[0:15], v[124:127], v[182:185], v[0:15]
	v_lshl_add_u64 v[210:211], v[210:211], 0, s[82:83]
	v_lshl_add_u64 v[212:213], v[212:213], 0, s[82:83]
	v_lshl_add_u64 v[214:215], v[214:215], 0, s[46:47]
	v_lshl_add_u64 v[216:217], v[216:217], 0, s[46:47]
	v_exp_f32_e32 v237, v237
	v_add_f32_e32 v204, v204, v236
	v_exp_f32_e32 v238, v238
	v_add_f32_e32 v205, v205, v237
	v_cvt_pk_bf16_f32 v233, v236, v237
	s_nop 1
	v_mfma_f32_32x32x16_bf16 v[16:31], v[196:199], v[230:233], v[16:31]
	v_exp_f32_e32 v239, v239
	v_add_f32_e32 v225, v225, v238
	v_exp_f32_e32 v240, v240
	v_add_f32_e32 v229, v229, v239
	v_cvt_pk_bf16_f32 v234, v238, v239
	v_exp_f32_e32 v241, v241
	v_add_f32_e32 v204, v204, v240
	v_exp_f32_e32 v242, v242
	v_add_f32_e32 v205, v205, v241
	v_cvt_pk_bf16_f32 v235, v240, v241
	v_mfma_f32_32x32x16_bf16 v[0:15], v[200:203], v[230:233], v[0:15]
	v_exp_f32_e32 v243, v243
	v_add_f32_e32 v225, v225, v242
	v_exp_f32_e32 v244, v244
	v_add_f32_e32 v229, v229, v243
	v_cvt_pk_bf16_f32 v236, v242, v243
	v_exp_f32_e32 v245, v245
	v_add_f32_e32 v204, v204, v244
	s_nop 0
	v_add_f32_e32 v205, v205, v245
	v_cvt_pk_bf16_f32 v237, v244, v245
	s_nop 1
	v_mfma_f32_32x32x16_bf16 v[16:31], v[246:249], v[234:237], v[16:31]
	v_add_f32_e32 v225, v225, v229
	v_add_f32_e32 v204, v204, v205
	v_add_f32_e32 v225, v225, v204
	v_add_f32_e32 v221, v221, v225
	v_mfma_f32_32x32x16_bf16 v[0:15], v[250:253], v[234:237], v[0:15]
	ds_read_b128 v[238:241], v222 offset:32
	ds_read_b128 v[242:245], v222 offset:6688
	s_add_u32 s20, s20, 1
	s_cbranch_scc0 .Lmla_top
	s_waitcnt lgkmcnt(0)
	v_mov_b32_e32 v96, v221
	s_branch .LBB0_1227
